# NSA phase: dynamic per-XCD ticket distribution of 32-token tiles (largest first) instead of the static item->workgroup schedule
# speedup vs baseline: 1.0908x; 1.0316x over previous
.LBB0_1464:
	s_or_b64 exec, exec, s[0:1]
	s_andn2_b64 vcc, exec, s[18:19]
	s_waitcnt lgkmcnt(0)
	s_barrier
	s_cbranch_vccnz .LBB0_1682
	s_add_u32 s100, s72, 0x2f80000
	s_addc_u32 s101, s73, 0
	s_mov_b32 s98, 0x2000
	s_mov_b32 s99, 0
	v_lshrrev_b32_e32 v244, 4, v220
	v_and_b32_e32 v245, 3, v244
	v_lshrrev_b32_e32 v246, 7, v220
	v_lshl_or_b32 v245, v246, 2, v245
	v_and_b32_e32 v246, 15, v220
	v_xor_b32_e32 v245, v245, v246
	v_lshlrev_b32_e32 v245, 4, v245
	v_lshl_or_b32 v249, v244, 8, v245
	v_xor_b32_e32 v250, 0x80, v249
	v_and_b32_e32 v245, 7, v244
	v_and_b32_e32 v246, 7, v220
	v_xor_b32_e32 v245, v245, v246
	v_lshlrev_b32_e32 v245, 4, v245
	v_lshrrev_b32_e32 v246, 3, v220
	v_lshl_or_b32 v251, v246, 7, v245
	v_lshlrev_b32_e32 v252, 4, v220
	v_add_u32_e32 v252, 0x1000, v252
	v_mov_b32_e32 v253, 0
	s_mov_b32 s57, 0
	s_cmpk_lg_i32 s74, 0x200
	s_mov_b32 s3, s57
	s_cselect_b64 s[52:53], -1, 0
	s_lshr_b32 s0, s2, 8
	s_lshl_b64 s[58:59], s[2:3], 8
	s_add_u32 s60, s72, 0x13200000
	s_addc_u32 s61, s73, 0
	s_add_u32 s62, s72, 0x3000000
	s_addc_u32 s63, s73, 0
	s_add_u32 s3, s72, 0x3600000
	s_addc_u32 s87, s73, 0
	s_add_u32 s88, s72, 0x3800000
	s_addc_u32 s89, s73, 0
	s_add_u32 s64, s72, 0x7200000
	s_addc_u32 s65, s73, 0
	s_add_u32 s90, s72, 0xb200000
	s_addc_u32 s91, s73, 0
	v_writelane_b32 v254, s54, 32
	s_add_u32 s92, s72, 0xd200000
	s_addc_u32 s93, s73, 0
	v_writelane_b32 v254, s55, 33
	v_writelane_b32 v254, s0, 24
	s_add_u32 s0, s72, 0x11200000
	v_writelane_b32 v254, s0, 22
	s_addc_u32 s0, s73, 0
	s_add_u32 s96, s72, 0xf200000
	s_addc_u32 s97, s73, 0
	s_movk_i32 s4, 0x1ff
	s_waitcnt vmcnt(15)
	v_mov_b32_e32 v168, 0x10200
	v_mov_b32_e32 v17, 0
	s_mov_b32 s5, 0x8000
	s_movk_i32 s8, 0x400
	s_movk_i32 s9, 0x7fff
	v_mov_b32_e32 v169, 0xf149f2ca
	v_mbcnt_hi_u32_b32 v170, -1, v221
	v_mov_b32_e32 v171, 0xc0
	v_mov_b32_e32 v172, 0x7149f200
	v_mov_b32_e32 v173, 0x7149f2ca
	v_mov_b32_e32 v174, 1
	s_mov_b32 s6, s2
	v_writelane_b32 v254, s0, 26
	s_branch .LBB0_1468

.LBB0_1468:
	v_mov_b32_e32 v0, v220
	v_cmp_eq_u32_e32 vcc, 0, v220
	s_and_saveexec_b64 s[0:1], vcc
	s_cbranch_execz .Lnsa_tk1
	s_and_b32 s7, s2, 7
	s_lshl_b32 s7, s7, 6
	v_mov_b32_e32 v2, s7
	v_mov_b32_e32 v1, 1
	global_atomic_add v1, v2, v1, s[100:101] sc0
	s_waitcnt vmcnt(0)
	v_mov_b32_e32 v2, 0x10608
	ds_write_b32 v2, v1
	s_waitcnt lgkmcnt(0)
.Lnsa_tk1:
	s_or_b64 exec, exec, s[0:1]
	s_barrier
	v_mov_b32_e32 v1, 0x10608
	ds_read_b32 v1, v1
	s_waitcnt lgkmcnt(0)
	s_nop 1
	v_readfirstlane_b32 s6, v1
	s_nop 3
	s_cmp_gt_u32 s6, 0x1ff
	s_cbranch_scc1 .LBB0_1681
	s_sub_i32 s50, 0x1ff, s6
	s_and_b32 s66, s2, 7
